# K/V projections as distributed 64x64 mini-GEMM on all workgroups (+ one L2 write-back per workgroup) on top of the group-barrier version
# speedup vs baseline: 1.0022x; 1.0022x over previous
.Llbf_done:
	v_readlane_b32 s0, v252, 34
	s_mov_b32 s98, 0
	s_cmp_lg_u32 s0, 0x100
	s_cbranch_scc1 .Lkv_done
	s_mov_b32 s98, 1
	v_readlane_b32 s0, v252, 0
	v_readlane_b32 s56, v252, 45
	v_readlane_b32 s57, v252, 46
	s_nop 0
	s_lshr_b32 s1, s0, 6
	s_and_b32 s4, s0, 63
	s_lshr_b32 s5, s1, 1
	s_and_b32 s10, s1, 1
	s_lshl_b32 s26, s5, 21
	s_add_u32 s28, s56, 0x300000
	s_addc_u32 s29, s57, 0
	s_add_u32 s28, s28, s26
	s_addc_u32 s29, s29, 0
	s_lshl_b32 s26, s5, 20
	s_add_u32 s30, s56, 0x4e00000
	s_addc_u32 s31, s57, 0
	s_add_u32 s30, s30, s26
	s_addc_u32 s31, s31, 0
	s_lshl_b32 s26, s5, 19
	s_cmp_eq_u32 s10, 0
	s_mov_b32 s27, 0x200000
	s_cselect_b32 s27, 0x100000, s27
	s_add_u32 s26, s26, s27
	s_add_u32 s36, s56, s26
	s_addc_u32 s37, s57, 0
	s_cmp_eq_u32 s10, 0
	s_cbranch_scc0 .Lkv_vtype
	s_mov_b64 s[44:45], s[28:29]
	s_mov_b64 s[46:47], s[30:31]
	s_movk_i32 s38, 0x200
	s_lshr_b32 s39, s4, 2
	s_and_b32 s48, s4, 3
	s_branch .Lkv_common

.Lkv_common:
	s_lshl_b32 s49, s39, 17
	s_add_u32 s44, s44, s49
	s_addc_u32 s45, s45, 0
	s_lshl_b32 s49, s48, 17
	s_add_u32 s46, s46, s49
	s_addc_u32 s47, s47, 0
	s_lshl_b32 s49, s38, 6
	s_mul_i32 s49, s49, s39
	s_lshl_b32 s55, s48, 7
	s_add_u32 s49, s49, s55
	s_add_u32 s36, s36, s49
	s_addc_u32 s37, s37, 0
	v_and_b32_e32 v0, 63, v241
	v_lshrrev_b32_e32 v1, 6, v241
	v_and_b32_e32 v20, 15, v0
	v_lshrrev_b32_e32 v21, 4, v0
	v_and_b32_e32 v22, 3, v1
	v_lshrrev_b32_e32 v23, 2, v1
	v_lshl_add_u32 v24, v22, 4, v20
	v_lshl_add_u32 v25, v23, 5, v20
	v_lshlrev_b32_e32 v26, 4, v21
	v_lshl_add_u32 v27, v24, 11, v26
	v_lshl_add_u32 v28, v25, 11, v26
	v_add_u32_e32 v29, 0x8000, v28
	v_mul_lo_u32 v30, v24, s38
	v_lshlrev_b32_e32 v31, 6, v23
	v_lshl_add_u32 v31, v21, 3, v31
	v_add_u32_e32 v30, v30, v31
	global_load_dwordx4 v[32:35], v27, s[44:45] offset:0
	global_load_dwordx4 v[36:39], v28, s[46:47] offset:0
	global_load_dwordx4 v[40:43], v29, s[46:47] offset:0
	global_load_dwordx4 v[44:47], v27, s[44:45] offset:64
	global_load_dwordx4 v[48:51], v28, s[46:47] offset:64
	global_load_dwordx4 v[52:55], v29, s[46:47] offset:64
	global_load_dwordx4 v[56:59], v27, s[44:45] offset:128
	global_load_dwordx4 v[60:63], v28, s[46:47] offset:128
	global_load_dwordx4 v[64:67], v29, s[46:47] offset:128
	global_load_dwordx4 v[68:71], v27, s[44:45] offset:192
	global_load_dwordx4 v[72:75], v28, s[46:47] offset:192
	global_load_dwordx4 v[76:79], v29, s[46:47] offset:192
	global_load_dwordx4 v[80:83], v27, s[44:45] offset:256
	global_load_dwordx4 v[84:87], v28, s[46:47] offset:256
	global_load_dwordx4 v[88:91], v29, s[46:47] offset:256
	global_load_dwordx4 v[92:95], v27, s[44:45] offset:320
	global_load_dwordx4 v[96:99], v28, s[46:47] offset:320
	global_load_dwordx4 v[100:103], v29, s[46:47] offset:320
	global_load_dwordx4 v[104:107], v27, s[44:45] offset:384
	global_load_dwordx4 v[108:111], v28, s[46:47] offset:384
	global_load_dwordx4 v[112:115], v29, s[46:47] offset:384
	global_load_dwordx4 v[116:119], v27, s[44:45] offset:448
	global_load_dwordx4 v[120:123], v28, s[46:47] offset:448
	global_load_dwordx4 v[124:127], v29, s[46:47] offset:448
	global_load_dwordx4 v[146:149], v27, s[44:45] offset:512
	global_load_dwordx4 v[150:153], v28, s[46:47] offset:512
	global_load_dwordx4 v[154:157], v29, s[46:47] offset:512
	global_load_dwordx4 v[158:161], v27, s[44:45] offset:576
	global_load_dwordx4 v[162:165], v28, s[46:47] offset:576
	global_load_dwordx4 v[166:169], v29, s[46:47] offset:576
	global_load_dwordx4 v[170:173], v27, s[44:45] offset:640
	global_load_dwordx4 v[174:177], v28, s[46:47] offset:640
	global_load_dwordx4 v[178:181], v29, s[46:47] offset:640
	global_load_dwordx4 v[182:185], v27, s[44:45] offset:704
	global_load_dwordx4 v[186:189], v28, s[46:47] offset:704
	global_load_dwordx4 v[190:193], v29, s[46:47] offset:704
	global_load_dwordx4 v[130:133], v27, s[44:45] offset:768
	global_load_dwordx4 v[134:137], v28, s[46:47] offset:768
	global_load_dwordx4 v[138:141], v29, s[46:47] offset:768
	global_load_dwordx4 v[194:197], v27, s[44:45] offset:832
	global_load_dwordx4 v[198:201], v28, s[46:47] offset:832
	global_load_dwordx4 v[202:205], v29, s[46:47] offset:832
	global_load_dwordx4 v[206:209], v27, s[44:45] offset:896
	global_load_dwordx4 v[210:213], v28, s[46:47] offset:896
	global_load_dwordx4 v[214:217], v29, s[46:47] offset:896
	global_load_dwordx4 v[218:221], v27, s[44:45] offset:960
	global_load_dwordx4 v[222:225], v28, s[46:47] offset:960
	global_load_dwordx4 v[226:229], v29, s[46:47] offset:960
	s_waitcnt vmcnt(36)
	v_mfma_f32_16x16x32_bf16 v[12:15], v[36:39], v[32:35], 0
	v_mfma_f32_16x16x32_bf16 v[16:19], v[40:43], v[32:35], 0
	v_mfma_f32_16x16x32_bf16 v[12:15], v[48:51], v[44:47], v[12:15]
	v_mfma_f32_16x16x32_bf16 v[16:19], v[52:55], v[44:47], v[16:19]
	v_mfma_f32_16x16x32_bf16 v[12:15], v[60:63], v[56:59], v[12:15]
	v_mfma_f32_16x16x32_bf16 v[16:19], v[64:67], v[56:59], v[16:19]
	v_mfma_f32_16x16x32_bf16 v[12:15], v[72:75], v[68:71], v[12:15]
	v_mfma_f32_16x16x32_bf16 v[16:19], v[76:79], v[68:71], v[16:19]
	global_load_dwordx4 v[32:35], v27, s[44:45] offset:1024
	global_load_dwordx4 v[36:39], v28, s[46:47] offset:1024
	global_load_dwordx4 v[40:43], v29, s[46:47] offset:1024
	global_load_dwordx4 v[44:47], v27, s[44:45] offset:1088
	global_load_dwordx4 v[48:51], v28, s[46:47] offset:1088
	global_load_dwordx4 v[52:55], v29, s[46:47] offset:1088
	global_load_dwordx4 v[56:59], v27, s[44:45] offset:1152
	global_load_dwordx4 v[60:63], v28, s[46:47] offset:1152
	global_load_dwordx4 v[64:67], v29, s[46:47] offset:1152
	global_load_dwordx4 v[68:71], v27, s[44:45] offset:1216
	global_load_dwordx4 v[72:75], v28, s[46:47] offset:1216
	global_load_dwordx4 v[76:79], v29, s[46:47] offset:1216
	s_waitcnt vmcnt(36)
	v_mfma_f32_16x16x32_bf16 v[12:15], v[84:87], v[80:83], v[12:15]
	v_mfma_f32_16x16x32_bf16 v[16:19], v[88:91], v[80:83], v[16:19]
	v_mfma_f32_16x16x32_bf16 v[12:15], v[96:99], v[92:95], v[12:15]
	v_mfma_f32_16x16x32_bf16 v[16:19], v[100:103], v[92:95], v[16:19]
	v_mfma_f32_16x16x32_bf16 v[12:15], v[108:111], v[104:107], v[12:15]
	v_mfma_f32_16x16x32_bf16 v[16:19], v[112:115], v[104:107], v[16:19]
	v_mfma_f32_16x16x32_bf16 v[12:15], v[120:123], v[116:119], v[12:15]
	v_mfma_f32_16x16x32_bf16 v[16:19], v[124:127], v[116:119], v[16:19]
	global_load_dwordx4 v[80:83], v27, s[44:45] offset:1280
	global_load_dwordx4 v[84:87], v28, s[46:47] offset:1280
	global_load_dwordx4 v[88:91], v29, s[46:47] offset:1280
	global_load_dwordx4 v[92:95], v27, s[44:45] offset:1344
	global_load_dwordx4 v[96:99], v28, s[46:47] offset:1344
	global_load_dwordx4 v[100:103], v29, s[46:47] offset:1344
	global_load_dwordx4 v[104:107], v27, s[44:45] offset:1408
	global_load_dwordx4 v[108:111], v28, s[46:47] offset:1408
	global_load_dwordx4 v[112:115], v29, s[46:47] offset:1408
	global_load_dwordx4 v[116:119], v27, s[44:45] offset:1472
	global_load_dwordx4 v[120:123], v28, s[46:47] offset:1472
	global_load_dwordx4 v[124:127], v29, s[46:47] offset:1472
	s_waitcnt vmcnt(36)
	v_mfma_f32_16x16x32_bf16 v[12:15], v[150:153], v[146:149], v[12:15]
	v_mfma_f32_16x16x32_bf16 v[16:19], v[154:157], v[146:149], v[16:19]
	v_mfma_f32_16x16x32_bf16 v[12:15], v[162:165], v[158:161], v[12:15]
	v_mfma_f32_16x16x32_bf16 v[16:19], v[166:169], v[158:161], v[16:19]
	v_mfma_f32_16x16x32_bf16 v[12:15], v[174:177], v[170:173], v[12:15]
	v_mfma_f32_16x16x32_bf16 v[16:19], v[178:181], v[170:173], v[16:19]
	v_mfma_f32_16x16x32_bf16 v[12:15], v[186:189], v[182:185], v[12:15]
	v_mfma_f32_16x16x32_bf16 v[16:19], v[190:193], v[182:185], v[16:19]
	global_load_dwordx4 v[146:149], v27, s[44:45] offset:1536
	global_load_dwordx4 v[150:153], v28, s[46:47] offset:1536
	global_load_dwordx4 v[154:157], v29, s[46:47] offset:1536
	global_load_dwordx4 v[158:161], v27, s[44:45] offset:1600
	global_load_dwordx4 v[162:165], v28, s[46:47] offset:1600
	global_load_dwordx4 v[166:169], v29, s[46:47] offset:1600
	global_load_dwordx4 v[170:173], v27, s[44:45] offset:1664
	global_load_dwordx4 v[174:177], v28, s[46:47] offset:1664
	global_load_dwordx4 v[178:181], v29, s[46:47] offset:1664
	global_load_dwordx4 v[182:185], v27, s[44:45] offset:1728
	global_load_dwordx4 v[186:189], v28, s[46:47] offset:1728
	global_load_dwordx4 v[190:193], v29, s[46:47] offset:1728
	s_waitcnt vmcnt(36)
	v_mfma_f32_16x16x32_bf16 v[12:15], v[134:137], v[130:133], v[12:15]
	v_mfma_f32_16x16x32_bf16 v[16:19], v[138:141], v[130:133], v[16:19]
	v_mfma_f32_16x16x32_bf16 v[12:15], v[198:201], v[194:197], v[12:15]
	v_mfma_f32_16x16x32_bf16 v[16:19], v[202:205], v[194:197], v[16:19]
	v_mfma_f32_16x16x32_bf16 v[12:15], v[210:213], v[206:209], v[12:15]
	v_mfma_f32_16x16x32_bf16 v[16:19], v[214:217], v[206:209], v[16:19]
	v_mfma_f32_16x16x32_bf16 v[12:15], v[222:225], v[218:221], v[12:15]
	v_mfma_f32_16x16x32_bf16 v[16:19], v[226:229], v[218:221], v[16:19]
	global_load_dwordx4 v[130:133], v27, s[44:45] offset:1792
	global_load_dwordx4 v[134:137], v28, s[46:47] offset:1792
	global_load_dwordx4 v[138:141], v29, s[46:47] offset:1792
	global_load_dwordx4 v[194:197], v27, s[44:45] offset:1856
	global_load_dwordx4 v[198:201], v28, s[46:47] offset:1856
	global_load_dwordx4 v[202:205], v29, s[46:47] offset:1856
	global_load_dwordx4 v[206:209], v27, s[44:45] offset:1920
	global_load_dwordx4 v[210:213], v28, s[46:47] offset:1920
	global_load_dwordx4 v[214:217], v29, s[46:47] offset:1920
	global_load_dwordx4 v[218:221], v27, s[44:45] offset:1984
	global_load_dwordx4 v[222:225], v28, s[46:47] offset:1984
	global_load_dwordx4 v[226:229], v29, s[46:47] offset:1984
	s_waitcnt vmcnt(36)
	v_mfma_f32_16x16x32_bf16 v[12:15], v[36:39], v[32:35], v[12:15]
	v_mfma_f32_16x16x32_bf16 v[16:19], v[40:43], v[32:35], v[16:19]
	v_mfma_f32_16x16x32_bf16 v[12:15], v[48:51], v[44:47], v[12:15]
	v_mfma_f32_16x16x32_bf16 v[16:19], v[52:55], v[44:47], v[16:19]
	v_mfma_f32_16x16x32_bf16 v[12:15], v[60:63], v[56:59], v[12:15]
	v_mfma_f32_16x16x32_bf16 v[16:19], v[64:67], v[56:59], v[16:19]
	v_mfma_f32_16x16x32_bf16 v[12:15], v[72:75], v[68:71], v[12:15]
	v_mfma_f32_16x16x32_bf16 v[16:19], v[76:79], v[68:71], v[16:19]
	s_waitcnt vmcnt(24)
	v_mfma_f32_16x16x32_bf16 v[12:15], v[84:87], v[80:83], v[12:15]
	v_mfma_f32_16x16x32_bf16 v[16:19], v[88:91], v[80:83], v[16:19]
	v_mfma_f32_16x16x32_bf16 v[12:15], v[96:99], v[92:95], v[12:15]
	v_mfma_f32_16x16x32_bf16 v[16:19], v[100:103], v[92:95], v[16:19]
	v_mfma_f32_16x16x32_bf16 v[12:15], v[108:111], v[104:107], v[12:15]
	v_mfma_f32_16x16x32_bf16 v[16:19], v[112:115], v[104:107], v[16:19]
	v_mfma_f32_16x16x32_bf16 v[12:15], v[120:123], v[116:119], v[12:15]
	v_mfma_f32_16x16x32_bf16 v[16:19], v[124:127], v[116:119], v[16:19]
	s_waitcnt vmcnt(12)
	v_mfma_f32_16x16x32_bf16 v[12:15], v[150:153], v[146:149], v[12:15]
	v_mfma_f32_16x16x32_bf16 v[16:19], v[154:157], v[146:149], v[16:19]
	v_mfma_f32_16x16x32_bf16 v[12:15], v[162:165], v[158:161], v[12:15]
	v_mfma_f32_16x16x32_bf16 v[16:19], v[166:169], v[158:161], v[16:19]
	v_mfma_f32_16x16x32_bf16 v[12:15], v[174:177], v[170:173], v[12:15]
	v_mfma_f32_16x16x32_bf16 v[16:19], v[178:181], v[170:173], v[16:19]
	v_mfma_f32_16x16x32_bf16 v[12:15], v[186:189], v[182:185], v[12:15]
	v_mfma_f32_16x16x32_bf16 v[16:19], v[190:193], v[182:185], v[16:19]
	s_waitcnt vmcnt(0)
	v_mfma_f32_16x16x32_bf16 v[12:15], v[134:137], v[130:133], v[12:15]
	v_mfma_f32_16x16x32_bf16 v[16:19], v[138:141], v[130:133], v[16:19]
	v_mfma_f32_16x16x32_bf16 v[12:15], v[198:201], v[194:197], v[12:15]
	v_mfma_f32_16x16x32_bf16 v[16:19], v[202:205], v[194:197], v[16:19]
	v_mfma_f32_16x16x32_bf16 v[12:15], v[210:213], v[206:209], v[12:15]
	v_mfma_f32_16x16x32_bf16 v[16:19], v[214:217], v[206:209], v[16:19]
	v_mfma_f32_16x16x32_bf16 v[12:15], v[222:225], v[218:221], v[12:15]
	v_mfma_f32_16x16x32_bf16 v[16:19], v[226:229], v[218:221], v[16:19]
	s_nop 7
	s_nop 3
	v_cvt_pk_bf16_f32 v20, v12, v13
	v_cvt_pk_bf16_f32 v21, v14, v15
	v_cvt_pk_bf16_f32 v22, v16, v17
	v_cvt_pk_bf16_f32 v23, v18, v19
	global_store_dwordx2 v30, v[20:21], s[36:37]
	global_store_dwordx2 v30, v[22:23], s[36:37] offset:32
	s_waitcnt vmcnt(0)
	s_barrier
	s_and_saveexec_b64 s[0:1], s[62:63]
	s_cbranch_execz .Lkv_nowb
	buffer_wbl2 sc1
	s_waitcnt vmcnt(0)
.Lkv_nowb:
	s_or_b64 exec, exec, s[0:1]
.Lkv_done:
	s_branch .LBB0_175

.LBB0_175:
	s_and_b32 s10, s54, 1
	s_cmp_eq_u32 s10, 0
	s_cselect_b64 s[4:5], -1, 0
	s_and_b64 s[0:1], s[4:5], exec
	s_cselect_b32 s55, 4, 1
	s_lshl_b32 s0, s54, 2
	s_sub_i32 s0, s6, s0
	s_ashr_i32 s1, s0, 31
	s_abs_i32 s0, s0
	s_mul_hi_u32 s26, s0, s51
	s_mul_i32 s26, s26, s50
	s_sub_i32 s0, s0, s26
	s_sub_i32 s26, s0, s50
	s_cmp_ge_u32 s0, s50
	s_cselect_b32 s0, s26, s0
	s_sub_i32 s26, s0, s50
	s_cmp_ge_u32 s0, s50
	s_cselect_b32 s0, s26, s0
	s_xor_b32 s0, s0, s1
	s_sub_i32 s56, s0, s1
	s_lshl_b32 s0, s10, 1
	s_lshl_b32 s36, s55, s0
	v_mov_b32_e32 v4, v241
	s_cmp_ge_i32 s56, s36
	v_readfirstlane_b32 s30, v4
	s_cbranch_scc1 .LBB0_174
	s_cmp_eq_u32 s98, 1
	s_cbranch_scc1 .LBB0_174
	s_ashr_i32 s59, s56, 31
	s_lshr_b32 s0, s59, 29
	s_add_i32 s27, s56, s0
	s_lshr_b32 s57, s36, 3
	s_and_b32 s0, s27, -8
	s_and_b32 s58, s36, 5
	s_sub_i32 s10, s56, s0
	s_or_b32 s60, s57, 1
	s_cmp_ge_i32 s10, s58
	s_mov_b64 s[0:1], -1
	s_mul_i32 s61, s60, s58
	s_cbranch_scc0 .LBB0_178
	s_sub_i32 s0, s10, s58
	s_mul_i32 s0, s0, s57
	s_add_i32 s26, s0, s61
	s_mov_b64 s[0:1], 0
